# u1 + the XCD leader no longer waits for its own release atomic before the closing workgroup barrier (the invalidate it used to cover now completes earlier)
# baseline (speedup 1.0000x reference)
.LBB0_145:
	s_or_b64 exec, exec, s[24:25]
.LBB0_146:
	s_or_b64 exec, exec, s[2:3]
	v_rsq_f32_e32 v134, v130
	v_rsq_f32_e32 v135, v131
	v_rsq_f32_e32 v132, v132
	v_rsq_f32_e32 v133, v133
	v_rsq_f32_e32 v130, v136
	v_rsq_f32_e32 v131, v137
	s_waitcnt lgkmcnt(0)
	v_rsq_f32_e32 v128, v138
	v_rsq_f32_e32 v129, v139
	v_mov_b32_e32 v144, v202
	s_movk_i32 s2, 0x400
	s_barrier
	s_nop 0
	v_cmp_gt_i32_e64 s[22:23], s2, v144
	s_barrier
	s_and_saveexec_b64 s[2:3], s[22:23]
	s_cbranch_execz .LBB0_154
	s_ashr_i32 s6, s96, 5
	v_max_i32_e32 v136, 0x200, v144
	s_mul_hi_i32 s7, s6, 0x3000
	s_mulk_i32 s6, 0x3000
	v_sub_u32_e32 v136, v136, v144
	s_add_u32 s6, s78, s6
	s_movk_i32 s24, 0x1ff
	v_add_u32_e32 v137, 0x1ff, v136
	s_addc_u32 s7, s79, s7
	v_cmp_lt_u32_e32 vcc, s24, v137
	s_mov_b64 s[26:27], -1
	v_mov_b32_e32 v136, v144
	s_and_saveexec_b64 s[24:25], vcc
	s_cbranch_execz .LBB0_151
	s_add_u32 s26, s6, 0x1000
	s_addc_u32 s27, s7, 0
	s_add_u32 s28, s6, 0x198000
	s_addc_u32 s29, s7, 0
	s_add_u32 s30, s6, 0x199000
	s_addc_u32 s31, s7, 0
	s_add_u32 s34, s6, 0x330000
	s_addc_u32 s35, s7, 0
	s_add_u32 s36, s6, 0x331000
	s_addc_u32 s37, s7, 0
	s_add_u32 s38, s6, 0x4c8000
	s_addc_u32 s39, s7, 0
	s_add_u32 s40, s6, 0x4c9000
	s_addc_u32 s41, s7, 0
	s_add_u32 s42, s6, 0x660000
	s_addc_u32 s43, s7, 0
	s_add_u32 s44, s6, 0x661000
	s_addc_u32 s45, s7, 0
	s_add_u32 s46, s6, 0x7f8000
	s_addc_u32 s47, s7, 0
	s_add_u32 s48, s6, 0x7f9000
	s_addc_u32 s49, s7, 0
	s_add_u32 s50, s6, 0x990000
	s_addc_u32 s51, s7, 0
	s_add_u32 s52, s6, 0x991000
	s_mov_b64 s[74:75], s[90:91]
	s_addc_u32 s53, s7, 0
	s_load_dwordx16 s[80:95], s[0:1], 0x0
	s_add_u32 s54, s6, 0xb28000
	v_lshrrev_b32_e32 v136, 9, v137
	s_addc_u32 s55, s7, 0
	v_add_u32_e32 v138, 1, v136
	s_add_u32 s68, s6, 0xb29000
	v_and_b32_e32 v139, 0xfffffe, v138
	v_add_u32_e32 v145, 0x200, v144
	s_addc_u32 s69, s7, 0
	v_lshl_add_u32 v141, v144, 2, 0
	s_mov_b64 s[70:71], 0
	s_movk_i32 s72, 0x1000
	v_mov_b32_e32 v140, v139
	v_mov_b64_e32 v[136:137], v[144:145]

.LBB0_214:
	s_or_b64 exec, exec, s[8:9]
.LBB0_215:
	v_writelane_b32 v234, s53, 20
	v_writelane_b32 v234, s52, 21
	v_writelane_b32 v234, s84, 22
	s_nop 1
	v_writelane_b32 v234, s85, 23
	v_writelane_b32 v234, s86, 24
	v_writelane_b32 v234, s87, 25
	v_writelane_b32 v234, s88, 26
	v_writelane_b32 v234, s89, 27
	v_writelane_b32 v234, s90, 28
	v_writelane_b32 v234, s91, 29
	s_or_b64 exec, exec, s[2:3]
	s_add_u32 s89, s78, 0x2dc8000
	s_addc_u32 s91, s79, 0
	s_add_u32 s70, s78, 0x3b08000
	s_addc_u32 s71, s79, 0
	s_add_u32 s72, s78, 0xefc8000
	s_addc_u32 s73, s79, 0
	s_add_u32 s0, s0, 0xb0
	s_addc_u32 s1, s1, 0
	s_add_u32 s80, s78, 0xefe8a00
	s_addc_u32 s81, s79, 0
	s_add_u32 s24, s78, 0xefe8c00
	s_addc_u32 s25, s79, 0
	s_add_u32 s20, s78, 0xefe8d00
	v_writelane_b32 v234, s0, 30
	s_addc_u32 s21, s79, 0
	s_mov_b64 s[16:17], -1
	v_writelane_b32 v234, s1, 31
	s_add_u32 s0, s78, 0xefe8e00
	s_addc_u32 s1, s79, 0
	v_writelane_b32 v234, s0, 32
	v_mov_b32_e32 v158, s96
	v_mov_b32_e32 v129, 0
	v_writelane_b32 v234, s1, 33
	s_add_u32 s0, s78, 0xefe8f00
	s_addc_u32 s1, s79, 0
	v_writelane_b32 v234, s0, 34
	s_mov_b64 s[82:83], 0x80
	s_mov_b32 s84, 0x3e6d3388
	v_writelane_b32 v234, s1, 35
	s_add_u32 s0, s78, 0xefe9000
	s_addc_u32 s1, s79, 0
	s_add_u32 s28, s78, 0xefe9100
	s_addc_u32 s29, s79, 0
	s_add_u32 s30, s78, 0xefe9200
	s_addc_u32 s31, s79, 0
	s_add_u32 s34, s78, 0xefe9300
	s_addc_u32 s35, s79, 0
	s_add_u32 s40, s78, 0xefe9400
	s_addc_u32 s41, s79, 0
	s_add_u32 s42, s78, 0xefe9500
	s_addc_u32 s43, s79, 0
	s_add_u32 s44, s78, 0xefe9600
	s_addc_u32 s45, s79, 0
	s_add_u32 s46, s78, 0xefe9700
	s_addc_u32 s47, s79, 0
	s_add_u32 s48, s78, 0xefe9800
	s_addc_u32 s49, s79, 0
	s_add_u32 s50, s78, 0xefe9900
	s_addc_u32 s51, s79, 0
	s_add_u32 s52, s78, 0xefe9a00
	s_addc_u32 s53, s79, 0
	s_add_u32 s54, s78, 0xefe9b00
	v_writelane_b32 v234, s0, 36
	s_addc_u32 s55, s79, 0
	s_mov_b32 s86, 0x3f07dc22
	v_writelane_b32 v234, s1, 37
	s_add_u32 s0, s78, 0xefebc00
	s_addc_u32 s1, s79, 0
	v_writelane_b32 v234, s0, 38
	s_add_u32 s22, s78, 0xefebd00
	s_addc_u32 s23, s79, 0
	v_writelane_b32 v234, s1, 39
	v_writelane_b32 v234, s96, 40
	s_add_i32 s0, 0, 0x20000
	v_writelane_b32 v234, s0, 41
	s_add_i32 s0, 0, 0x20004
	v_writelane_b32 v234, s0, 42
	v_writelane_b32 v234, s80, 43
	s_mov_b32 s88, 0xbf3a00e3
	s_mov_b32 s90, 0x3f35f0e3
	v_writelane_b32 v234, s81, 44
	v_writelane_b32 v234, s22, 45
	s_mov_b32 s92, 0xbe11a98e
	s_mov_b32 s94, 0x3e027906
	v_writelane_b32 v234, s23, 46
	v_writelane_b32 v234, s24, 47
	s_mov_b32 s96, 0xbf38aa3b
	v_mov_b32_e32 v159, 0x1000
	v_writelane_b32 v234, s25, 48
	v_mov_b32_e32 v160, 0x2000
	v_mov_b32_e32 v161, 1
	v_writelane_b32 v234, s20, 49
	s_waitcnt lgkmcnt(0)
	s_barrier
	v_writelane_b32 v234, s21, 50
	s_branch .LBB0_219
.LBB0_216:
	s_or_b64 exec, exec, s[6:7]
.LBB0_217:
	s_or_b64 exec, exec, s[0:1]
	s_mov_b64 s[0:1], 0
	s_waitcnt lgkmcnt(0)
	s_barrier

.LBB0_798:
	s_or_b64 exec, exec, s[8:9]
.LBB0_799:
	s_or_b64 exec, exec, s[0:1]
	s_cmpk_lt_i32 s92, 0x100
	s_cselect_b64 s[6:7], -1, 0
	s_waitcnt lgkmcnt(0)
	v_mov_b32_e32 v0, v202
	s_and_b64 vcc, exec, s[6:7]
	s_barrier
	s_cbranch_vccnz .LBB0_801
	s_load_dword s12, s[88:89], 0x0
	s_cbranch_execz .LBB0_802
	s_branch .LBB0_808

.LBB0_873:
	s_or_b64 exec, exec, s[8:9]
.LBB0_874:
	s_or_b64 exec, exec, s[0:1]
	s_waitcnt lgkmcnt(0)
	v_mov_b32_e32 v0, v202
	s_andn2_b64 vcc, exec, s[6:7]
	s_barrier
	s_cbranch_vccnz .LBB0_881
	v_lshlrev_b32_e32 v2, 1, v0
	v_and_b32_e32 v2, 0xffffff00, v2
	v_ashrrev_i32_e32 v3, 31, v2
	v_and_b32_e32 v72, 48, v0
	v_mov_b32_e32 v73, 0
	v_lshl_add_u64 v[2:3], v[2:3], 1, s[78:79]
	v_and_b32_e32 v1, 63, v0
	v_and_b32_e32 v80, 15, v0
	v_bfe_u32 v81, v0, 4, 2
	v_ashrrev_i32_e32 v4, 6, v0
	v_lshl_add_u64 v[2:3], v[2:3], 0, v[72:73]
	s_mov_b64 s[0:1], 0xef88000
	v_lshl_add_u32 v82, v0, 4, 0
	v_and_b32_e32 v0, 0xfffffc0, v0
	v_lshlrev_b32_e32 v5, 4, v4
	v_lshl_add_u64 v[74:75], v[2:3], 0, s[0:1]
	s_mov_b64 s[0:1], 0x38c8000
	v_lshlrev_b32_e32 v0, 4, v0
	v_lshlrev_b32_e32 v1, 4, v1
	s_add_u32 s2, s78, 0xeec8000
	v_lshl_add_u64 v[76:77], v[2:3], 0, s[0:1]
	v_cmp_gt_i32_e64 s[0:1], 2, v4
	v_add3_u32 v83, 0, v0, v1
	s_addc_u32 s3, s79, 0
	v_and_or_b32 v84, v5, 16, v80
	s_lshl_b32 s6, s92, 2
	s_lshl_b32 s7, s12, 2
	s_lshl_b32 s8, s92, 5
	s_lshl_b32 s9, s12, 5
	s_mov_b32 s13, s92
	s_branch .LBB0_877

.LBB0_970:
	s_or_b64 exec, exec, s[10:11]
.LBB0_971:
	s_or_b64 exec, exec, s[6:7]
